# v57: v50 + final RMSNorm rows software-pipelined (next row's x loads issued before the current row's stores; gain vector hoisted)
# baseline (speedup 1.0000x reference)
.LBB0_321:
	s_or_b64 exec, exec, s[6:7]
	s_movk_i32 s14, 0x800
	v_cmp_gt_u32_e64 s[12:13], s14, v0
	s_nop 1
	s_cmp_lg_u64 s[12:13], 0
	s_cbranch_scc0 .Lfn_pipe
	v_lshl_add_u64 v[14:15], v[14:15], 0, v[10:11]
	global_load_dwordx4 v[24:27], v[14:15], off
	global_load_dwordx4 v[28:31], v[14:15], off offset:1024
	global_load_dwordx4 v[32:35], v[14:15], off offset:3072
	global_load_dwordx4 v[36:39], v[14:15], off offset:2048
	s_branch .Lfn_have
.Lfn_pipe:
	s_waitcnt vmcnt(4)
	v_mov_b32_e32 v24, v72
	v_mov_b32_e32 v25, v73
	v_mov_b32_e32 v26, v74
	v_mov_b32_e32 v27, v75
	v_mov_b32_e32 v28, v76
	v_mov_b32_e32 v29, v77
	v_mov_b32_e32 v30, v78
	v_mov_b32_e32 v31, v79
	v_mov_b32_e32 v32, v80
	v_mov_b32_e32 v33, v81
	v_mov_b32_e32 v34, v82
	v_mov_b32_e32 v35, v83
	v_mov_b32_e32 v36, v84
	v_mov_b32_e32 v37, v85
	v_mov_b32_e32 v38, v86
	v_mov_b32_e32 v39, v87
.Lfn_have:
	v_add_u32_e32 v0, s28, v0
	v_lshl_add_u64 v[8:9], v[8:9], 0, s[98:99]
	v_min_u32_e32 v88, 0x2fff, v0
	v_mov_b32_e32 v89, 0
	v_lshlrev_b64 v[88:89], 12, v[88:89]
	v_lshl_add_u64 v[88:89], s[0:1], 0, v[88:89]
	v_lshl_add_u64 v[88:89], v[88:89], 0, v[10:11]
	global_load_dwordx4 v[72:75], v[88:89], off
	global_load_dwordx4 v[76:79], v[88:89], off offset:1024
	global_load_dwordx4 v[80:83], v[88:89], off offset:3072
	global_load_dwordx4 v[84:87], v[88:89], off offset:2048
	s_waitcnt vmcnt(7)
	v_pk_mul_f32 v[14:15], v[26:27], v[26:27]
	v_pk_mul_f32 v[44:45], v[24:25], v[24:25]
	s_waitcnt vmcnt(6)
	v_pk_mul_f32 v[46:47], v[30:31], v[30:31]
	v_pk_mul_f32 v[48:49], v[28:29], v[28:29]
	v_pk_mov_b32 v[52:53], v[44:45], v[14:15] op_sel:[1,0]
	v_mov_b32_e32 v45, v15
	v_pk_mov_b32 v[14:15], v[48:49], v[46:47] op_sel:[1,0]
	v_mov_b32_e32 v49, v47
	s_waitcnt vmcnt(4)
	v_mul_f32_e32 v2, v37, v37
	v_mul_f32_e32 v50, v39, v39
	v_pk_add_f32 v[44:45], v[52:53], v[44:45]
	v_pk_add_f32 v[14:15], v[14:15], v[48:49]
	v_mul_f32_e32 v1, v32, v32
	v_mul_f32_e32 v23, v33, v33
	v_mul_f32_e32 v54, v34, v34
	v_mul_f32_e32 v55, v35, v35
	v_pk_fma_f32 v[46:47], v[36:37], v[36:37], v[2:3] op_sel_hi:[1,1,0]
	v_pk_fma_f32 v[50:51], v[38:39], v[38:39], v[50:51] op_sel_hi:[1,1,0]
	v_pk_add_f32 v[44:45], v[44:45], v[44:45] op_sel:[0,1] op_sel_hi:[1,0]
	v_pk_add_f32 v[14:15], v[14:15], v[14:15] op_sel:[0,1] op_sel_hi:[1,0]
	v_mov_b32_e32 v47, v54
	v_mov_b32_e32 v51, v55
	v_mov_b32_e32 v45, v1
	v_mov_b32_e32 v15, v23
	v_pk_add_f32 v[46:47], v[46:47], v[50:51]
	v_pk_add_f32 v[14:15], v[44:45], v[14:15]
	v_lshl_add_u64 v[44:45], v[6:7], 0, v[12:13]
	v_pk_add_f32 v[14:15], v[14:15], v[46:47]
	s_nop 0
	v_add_f32_e32 v1, v14, v15
	ds_bpermute_b32 v2, v16, v1
	s_waitcnt lgkmcnt(0)
	v_add_f32_e32 v1, v1, v2
	ds_bpermute_b32 v2, v17, v1
	s_waitcnt lgkmcnt(0)
	v_add_f32_e32 v1, v1, v2
	ds_bpermute_b32 v2, v18, v1
	s_waitcnt lgkmcnt(0)
	v_add_f32_e32 v1, v1, v2
	ds_bpermute_b32 v2, v19, v1
	s_waitcnt lgkmcnt(0)
	v_add_f32_e32 v1, v1, v2
	ds_bpermute_b32 v2, v20, v1
	s_waitcnt lgkmcnt(0)
	v_add_f32_e32 v1, v1, v2
	ds_bpermute_b32 v2, v21, v1
	s_waitcnt lgkmcnt(0)
	v_add_f32_e32 v1, v1, v2
	v_fmamk_f32 v1, v1, 0x3a800000, v22
	v_mul_f32_e32 v2, 0x4b800000, v1
	v_cmp_gt_f32_e32 vcc, s9, v1
	s_nop 1
	v_cndmask_b32_e32 v1, v1, v2, vcc
	v_rsq_f32_e32 v1, v1
	s_nop 0
	v_mul_f32_e32 v2, 0x45800000, v1
	v_cndmask_b32_e32 v2, v1, v2, vcc
	v_pk_mul_f32 v[12:13], v[24:25], v[2:3] op_sel_hi:[1,0]
	v_pk_mul_f32 v[14:15], v[26:27], v[2:3] op_sel_hi:[1,0]
	v_pk_mul_f32 v[12:13], v[56:57], v[12:13]
	v_pk_mul_f32 v[14:15], v[58:59], v[14:15]
	global_store_dwordx4 v[44:45], v[12:15], off
	v_pk_mul_f32 v[24:25], v[30:31], v[2:3] op_sel_hi:[1,0]
	v_pk_mul_f32 v[26:27], v[28:29], v[2:3] op_sel_hi:[1,0]
	v_cmp_lt_i32_e32 vcc, s10, v0
	s_or_b64 s[4:5], vcc, s[4:5]
	v_pk_mul_f32 v[12:13], v[60:61], v[26:27]
	v_pk_mul_f32 v[14:15], v[62:63], v[24:25]
	global_store_dwordx4 v[44:45], v[12:15], off offset:1024
	v_pk_mul_f32 v[24:25], v[38:39], v[2:3] op_sel_hi:[1,0]
	v_pk_mul_f32 v[26:27], v[36:37], v[2:3] op_sel_hi:[1,0]
	s_nop 0
	v_pk_mul_f32 v[14:15], v[66:67], v[24:25]
	v_pk_mul_f32 v[12:13], v[64:65], v[26:27]
	global_store_dwordx4 v[44:45], v[12:15], off offset:2048
	v_pk_mul_f32 v[24:25], v[34:35], v[2:3] op_sel_hi:[1,0]
	v_pk_mul_f32 v[26:27], v[32:33], v[2:3] op_sel_hi:[1,0]
	s_nop 0
	v_pk_mul_f32 v[14:15], v[70:71], v[24:25]
	v_pk_mul_f32 v[12:13], v[68:69], v[26:27]
	global_store_dwordx4 v[44:45], v[12:15], off offset:3072
	s_andn2_b64 exec, exec, s[4:5]
	s_cbranch_execz .LBB0_326
